# baseline (speedup 1.0000x reference)
; #define STAGE(PP, RSRC, br, kt) do { const int _so = ((br) * K + (kt) * BK) * 2; \
;       __builtin_amdgcn_raw_ptr_buffer_load_lds(RSRC, LDSP((char*)(PP) + ldsoff), 16, voff0, _so, 0, 0); \
;       __builtin_amdgcn_raw_ptr_buffer_load_lds(RSRC, LDSP((char*)(PP) + ldsoff + 8192), 16, voff1, _so, 0, 0); \
;     } while (0)
; #define LDA(dst, b, h) for (int m = 0; m < 4; ++m) for (int k = 0; k < 2; ++k) \
;     dst[m][k] = *reinterpret_cast<const bf16x8*>((char*)SA(b, h) + lds_byte(wr * 64 + m * 16 + fr, k * 32 + fq * 8))
; #define LDB(dst, b, h) for (int n = 0; n < 2; ++n) for (int k = 0; k < 2; ++k) \
;     dst[n][k] = *reinterpret_cast<const bf16x8*>((char*)SB(b, h) + lds_byte(wc * 32 + n * 16 + fr, k * 32 + fq * 8))
; #define MMA(ai, bj, At_, Bt_) do { __builtin_amdgcn_s_setprio(1); \
;     for (int m = 0; m < 4; ++m) for (int n = 0; n < 2; ++n) for (int k = 0; k < 2; ++k) \
;       acc[ai][bj][m][n] = __builtin_amdgcn_mfma_f32_16x16x32_bf16(At_[m][k], Bt_[n][k], acc[ai][bj][m][n], 0, 0, 0); \
;     __builtin_amdgcn_s_setprio(0); } while (0)
; #define WAIT_V(n) asm volatile("s_waitcnt vmcnt(" #n ")" ::: "memory")
; #define WAIT_L(n) asm volatile("s_waitcnt lgkmcnt(" #n ")" ::: "memory")
; #define BAR __builtin_amdgcn_s_barrier()
; #define SCHED __builtin_amdgcn_sched_barrier(0)
; __device__ __forceinline__ void gemm_tile(const Params& P, const GArgs& ga, const TileDesc& td, int wid_s) {
;     ...
;   for (int t = 0; t < nt - 2; t += 2) {
;     LDA(At, 0, 0); STAGE(SA(1, 1), A, brow + HALF, t + 1);
;     WAIT_L(8); BAR; WAIT_L(0); MMA(0, 0, At, B0); BAR; SCHED;
;     LDB(B1, 0, 1); STAGE(SB(0, 0), Bt, bcol, t + 2);
;     BAR; WAIT_L(0); MMA(0, 1, At, B1); BAR;
;     LDA(At, 0, 1); STAGE(SA(0, 0), A, brow, t + 2);
;     WAIT_V(4); BAR; WAIT_L(0); MMA(1, 0, At, B0); BAR; SCHED;
;     LDB(B0, 1, 0); STAGE(SB(0, 1), Bt, bcol + HALF, t + 2);
;     BAR; MMA(1, 1, At, B1); BAR;
;     LDA(At, 1, 0); STAGE(SA(0, 1), A, brow + HALF, t + 2);
;     WAIT_L(8); BAR; WAIT_L(0); MMA(0, 0, At, B0); BAR; SCHED;
;     LDB(B1, 1, 1); STAGE(SB(1, 0), Bt, bcol, t + 3);
;     BAR; WAIT_L(0); MMA(0, 1, At, B1); BAR;
;     LDA(At, 1, 1); STAGE(SA(1, 0), A, brow, t + 3);
;     WAIT_V(4); BAR; WAIT_L(0); MMA(1, 0, At, B0); BAR; SCHED;
;     LDB(B0, 0, 0); STAGE(SB(1, 1), Bt, bcol + HALF, t + 3);
;     BAR; MMA(1, 1, At, B1); BAR;
;   }
.LBB0_308:
	s_add_i32 s38, s1, s99
	s_add_i32 s6, s38, 0x80
	s_mov_b32 m0, s23
	ds_read_b128 v[170:173], v163
	ds_read_b128 v[174:177], v163 offset:1024
	ds_read_b128 v[178:181], v164
	ds_read_b128 v[182:185], v164 offset:1024
	ds_read_b128 v[186:189], v165
	ds_read_b128 v[190:193], v165 offset:1024
	ds_read_b128 v[194:197], v166
	ds_read_b128 v[204:207], v166 offset:1024
	buffer_load_dwordx4 v148, s[8:11], s6 offen lds
	s_mov_b32 m0, s22
	s_nop 0
	buffer_load_dwordx4 v149, s[8:11], s6 offen lds
	s_mul_i32 s6, s49, s15
	s_add_i32 s58, s6, s99
	s_mov_b32 m0, s88
	s_add_i32 vcc_hi, s58, 0x100
	s_mov_b32 s6, s10
	s_mov_b32 s7, s11
	ds_read_b128 v[208:211], v167
	ds_read_b128 v[212:215], v167 offset:1024
	ds_read_b128 v[216:219], v167 offset:2048
	ds_read_b128 v[220:223], v167 offset:3072
	buffer_load_dwordx4 v148, s[4:7], vcc_hi offen lds
	s_mov_b32 m0, s89
	s_add_i32 vcc_lo, vcc_lo, 2
	buffer_load_dwordx4 v149, s[4:7], vcc_hi offen lds
	s_waitcnt lgkmcnt(0)
	s_setprio 1
	s_barrier
	v_mfma_f32_16x16x32_bf16 v[138:141], v[170:173], v[2:5], v[138:141]
	v_mfma_f32_16x16x32_bf16 v[142:145], v[170:173], v[10:13], v[142:145]
	v_mfma_f32_16x16x32_bf16 v[134:137], v[178:181], v[2:5], v[134:137]
	v_mfma_f32_16x16x32_bf16 v[130:133], v[178:181], v[10:13], v[130:133]
	v_mfma_f32_16x16x32_bf16 v[126:129], v[186:189], v[2:5], v[126:129]
	v_mfma_f32_16x16x32_bf16 v[122:125], v[186:189], v[10:13], v[122:125]
	v_mfma_f32_16x16x32_bf16 v[118:121], v[194:197], v[2:5], v[118:121]
	v_mfma_f32_16x16x32_bf16 v[114:117], v[194:197], v[10:13], v[114:117]
	v_mfma_f32_16x16x32_bf16 v[138:141], v[174:177], v[6:9], v[138:141]
	v_mfma_f32_16x16x32_bf16 v[142:145], v[174:177], v[14:17], v[142:145]
	v_mfma_f32_16x16x32_bf16 v[134:137], v[182:185], v[6:9], v[134:137]
	v_mfma_f32_16x16x32_bf16 v[130:133], v[182:185], v[14:17], v[130:133]
	v_mfma_f32_16x16x32_bf16 v[126:129], v[190:193], v[6:9], v[126:129]
	v_mfma_f32_16x16x32_bf16 v[122:125], v[190:193], v[14:17], v[122:125]
	v_mfma_f32_16x16x32_bf16 v[118:121], v[204:207], v[6:9], v[118:121]
	v_mfma_f32_16x16x32_bf16 v[114:117], v[204:207], v[14:17], v[114:117]
	v_mfma_f32_16x16x32_bf16 v[110:113], v[170:173], v[208:211], v[110:113]
	v_mfma_f32_16x16x32_bf16 v[106:109], v[170:173], v[216:219], v[106:109]
	v_mfma_f32_16x16x32_bf16 v[102:105], v[178:181], v[208:211], v[102:105]
	v_mfma_f32_16x16x32_bf16 v[98:101], v[178:181], v[216:219], v[98:101]
	v_mfma_f32_16x16x32_bf16 v[94:97], v[186:189], v[208:211], v[94:97]
	v_mfma_f32_16x16x32_bf16 v[90:93], v[186:189], v[216:219], v[90:93]
	v_mfma_f32_16x16x32_bf16 v[86:89], v[194:197], v[208:211], v[86:89]
	v_mfma_f32_16x16x32_bf16 v[82:85], v[194:197], v[216:219], v[82:85]
	v_mfma_f32_16x16x32_bf16 v[110:113], v[174:177], v[212:215], v[110:113]
	v_mfma_f32_16x16x32_bf16 v[106:109], v[174:177], v[220:223], v[106:109]
	v_mfma_f32_16x16x32_bf16 v[102:105], v[182:185], v[212:215], v[102:105]
	v_mfma_f32_16x16x32_bf16 v[98:101], v[182:185], v[220:223], v[98:101]
	v_mfma_f32_16x16x32_bf16 v[94:97], v[190:193], v[212:215], v[94:97]
	v_mfma_f32_16x16x32_bf16 v[90:93], v[190:193], v[220:223], v[90:93]
	v_mfma_f32_16x16x32_bf16 v[86:89], v[204:207], v[212:215], v[86:89]
	v_mfma_f32_16x16x32_bf16 v[82:85], v[204:207], v[220:223], v[82:85]
	s_waitcnt vmcnt(8)
	s_barrier
	s_setprio 0
	s_mul_i32 vcc_hi, s49, s86
	s_add_i32 s40, vcc_hi, s99
	s_add_i32 vcc_hi, s40, 0x100
	s_mov_b32 m0, s52
	ds_read_b128 v[170:173], v163 offset:16384
	ds_read_b128 v[174:177], v163 offset:17408
	ds_read_b128 v[178:181], v164 offset:16384
	ds_read_b128 v[182:185], v164 offset:17408
	ds_read_b128 v[186:189], v165 offset:16384
	ds_read_b128 v[190:193], v165 offset:17408
	ds_read_b128 v[194:197], v166 offset:16384
	ds_read_b128 v[204:207], v166 offset:17408
	buffer_load_dwordx4 v148, s[8:11], vcc_hi offen lds
	s_mov_b32 m0, s94
	s_nop 0
	buffer_load_dwordx4 v149, s[8:11], vcc_hi offen lds
	s_add_i32 s33, s98, s99
	s_add_i32 vcc_hi, s33, 0x100
	s_mov_b32 m0, s95
	ds_read_b128 v[232:235], v168
	ds_read_b128 v[236:239], v168 offset:1024
	ds_read_b128 v[240:243], v168 offset:2048
	ds_read_b128 v[244:247], v168 offset:3072
	buffer_load_dwordx4 v148, s[4:7], vcc_hi offen lds
	s_mov_b32 m0, s3
	s_nop 0
	buffer_load_dwordx4 v149, s[4:7], vcc_hi offen lds
	s_waitcnt lgkmcnt(0)
	s_setprio 1
	s_barrier
	v_mfma_f32_16x16x32_bf16 v[78:81], v[170:173], v[2:5], v[78:81]
	v_mfma_f32_16x16x32_bf16 v[70:73], v[178:181], v[2:5], v[70:73]
	v_mfma_f32_16x16x32_bf16 v[62:65], v[186:189], v[2:5], v[62:65]
	v_mfma_f32_16x16x32_bf16 v[248:251], v[194:197], v[2:5], v[54:57]
	v_mfma_f32_16x16x32_bf16 v[78:81], v[174:177], v[6:9], v[78:81]
	v_mfma_f32_16x16x32_bf16 v[74:77], v[170:173], v[10:13], v[74:77]
	v_mfma_f32_16x16x32_bf16 v[70:73], v[182:185], v[6:9], v[70:73]
	v_mfma_f32_16x16x32_bf16 v[66:69], v[178:181], v[10:13], v[66:69]
	v_mfma_f32_16x16x32_bf16 v[62:65], v[190:193], v[6:9], v[62:65]
	v_mfma_f32_16x16x32_bf16 v[58:61], v[186:189], v[10:13], v[58:61]
	v_mfma_f32_16x16x32_bf16 v[248:251], v[204:207], v[6:9], v[248:251]
	v_mfma_f32_16x16x32_bf16 v[252:255], v[194:197], v[10:13], v[50:53]
	v_mfma_f32_16x16x32_bf16 v[74:77], v[174:177], v[14:17], v[74:77]
	v_mfma_f32_16x16x32_bf16 v[66:69], v[182:185], v[14:17], v[66:69]
	v_mfma_f32_16x16x32_bf16 v[58:61], v[190:193], v[14:17], v[58:61]
	v_mfma_f32_16x16x32_bf16 v[252:255], v[204:207], v[14:17], v[252:255]
	v_mfma_f32_16x16x32_bf16 v[46:49], v[170:173], v[208:211], v[46:49]
	v_mfma_f32_16x16x32_bf16 v[42:45], v[170:173], v[216:219], v[42:45]
	v_mfma_f32_16x16x32_bf16 v[38:41], v[178:181], v[208:211], v[38:41]
	v_mfma_f32_16x16x32_bf16 v[34:37], v[178:181], v[216:219], v[34:37]
	v_mfma_f32_16x16x32_bf16 v[30:33], v[186:189], v[208:211], v[30:33]
	v_mfma_f32_16x16x32_bf16 v[26:29], v[186:189], v[216:219], v[26:29]
	v_mfma_f32_16x16x32_bf16 v[22:25], v[194:197], v[208:211], v[22:25]
	v_mfma_f32_16x16x32_bf16 v[18:21], v[194:197], v[216:219], v[18:21]
	v_mfma_f32_16x16x32_bf16 v[46:49], v[174:177], v[212:215], v[46:49]
	v_mfma_f32_16x16x32_bf16 v[42:45], v[174:177], v[220:223], v[42:45]
	v_mfma_f32_16x16x32_bf16 v[38:41], v[182:185], v[212:215], v[38:41]
	v_mfma_f32_16x16x32_bf16 v[34:37], v[182:185], v[220:223], v[34:37]
	v_mfma_f32_16x16x32_bf16 v[30:33], v[190:193], v[212:215], v[30:33]
	v_mfma_f32_16x16x32_bf16 v[26:29], v[190:193], v[220:223], v[26:29]
	v_mfma_f32_16x16x32_bf16 v[22:25], v[204:207], v[212:215], v[22:25]
	v_mfma_f32_16x16x32_bf16 v[18:21], v[204:207], v[220:223], v[18:21]
	s_waitcnt vmcnt(8)
	s_barrier
; #define STAGE(PP, RSRC, br, kt) do { const int _so = ((br) * K + (kt) * BK) * 2; \
;       __builtin_amdgcn_raw_ptr_buffer_load_lds(RSRC, LDSP((char*)(PP) + ldsoff), 16, voff0, _so, 0, 0); \
;       __builtin_amdgcn_raw_ptr_buffer_load_lds(RSRC, LDSP((char*)(PP) + ldsoff + 8192), 16, voff1, _so, 0, 0); \
;     } while (0)
; #define LDA(dst, b, h) for (int m = 0; m < 4; ++m) for (int k = 0; k < 2; ++k) \
;     dst[m][k] = *reinterpret_cast<const bf16x8*>((char*)SA(b, h) + lds_byte(wr * 64 + m * 16 + fr, k * 32 + fq * 8))
; #define LDB(dst, b, h) for (int n = 0; n < 2; ++n) for (int k = 0; k < 2; ++k) \
;     dst[n][k] = *reinterpret_cast<const bf16x8*>((char*)SB(b, h) + lds_byte(wc * 32 + n * 16 + fr, k * 32 + fq * 8))
; #define MMA(ai, bj, At_, Bt_) do { __builtin_amdgcn_s_setprio(1); \
;     for (int m = 0; m < 4; ++m) for (int n = 0; n < 2; ++n) for (int k = 0; k < 2; ++k) \
;       acc[ai][bj][m][n] = __builtin_amdgcn_mfma_f32_16x16x32_bf16(At_[m][k], Bt_[n][k], acc[ai][bj][m][n], 0, 0, 0); \
;     __builtin_amdgcn_s_setprio(0); } while (0)
; #define WAIT_V(n) asm volatile("s_waitcnt vmcnt(" #n ")" ::: "memory")
; #define WAIT_L(n) asm volatile("s_waitcnt lgkmcnt(" #n ")" ::: "memory")
; #define BAR __builtin_amdgcn_s_barrier()
; #define SCHED __builtin_amdgcn_sched_barrier(0)
; __device__ __forceinline__ void gemm_tile(const Params& P, const GArgs& ga, const TileDesc& td, int wid_s) {
;     ...
;   for (int t = 0; t < nt - 2; t += 2) {
;     LDA(At, 0, 0); STAGE(SA(1, 1), A, brow + HALF, t + 1);
;     WAIT_L(8); BAR; WAIT_L(0); MMA(0, 0, At, B0); BAR; SCHED;
;     LDB(B1, 0, 1); STAGE(SB(0, 0), Bt, bcol, t + 2);
;     BAR; WAIT_L(0); MMA(0, 1, At, B1); BAR;
;     LDA(At, 0, 1); STAGE(SA(0, 0), A, brow, t + 2);
;     WAIT_V(4); BAR; WAIT_L(0); MMA(1, 0, At, B0); BAR; SCHED;
;     LDB(B0, 1, 0); STAGE(SB(0, 1), Bt, bcol + HALF, t + 2);
;     BAR; MMA(1, 1, At, B1); BAR;
;     LDA(At, 1, 0); STAGE(SA(0, 1), A, brow + HALF, t + 2);
;     WAIT_L(8); BAR; WAIT_L(0); MMA(0, 0, At, B0); BAR; SCHED;
;     LDB(B1, 1, 1); STAGE(SB(1, 0), Bt, bcol, t + 3);
;     BAR; WAIT_L(0); MMA(0, 1, At, B1); BAR;
;     LDA(At, 1, 1); STAGE(SA(1, 0), A, brow, t + 3);
;     WAIT_V(4); BAR; WAIT_L(0); MMA(1, 0, At, B0); BAR; SCHED;
;     LDB(B0, 0, 0); STAGE(SB(1, 1), Bt, bcol + HALF, t + 3);
;     BAR; MMA(1, 1, At, B1); BAR;
;   }
	s_setprio 0
	s_addk_i32 s38, 0x100
	s_mov_b32 m0, s57
	ds_read_b128 v[54:57], v163 offset:32768
	ds_read_b128 v[170:173], v163 offset:33792
	ds_read_b128 v[174:177], v164 offset:32768
	ds_read_b128 v[178:181], v164 offset:33792
	ds_read_b128 v[182:185], v165 offset:32768
	ds_read_b128 v[186:189], v165 offset:33792
	ds_read_b128 v[190:193], v166 offset:32768
	ds_read_b128 v[194:197], v166 offset:33792
	buffer_load_dwordx4 v148, s[8:11], s38 offen lds
	s_mov_b32 m0, s56
	s_nop 0
	buffer_load_dwordx4 v149, s[8:11], s38 offen lds
	s_addk_i32 s58, 0x180
	s_mov_b32 m0, s75
	ds_read_b128 v[204:207], v169
	ds_read_b128 v[208:211], v169 offset:1024
	ds_read_b128 v[212:215], v169 offset:2048
	ds_read_b128 v[216:219], v169 offset:3072
	buffer_load_dwordx4 v148, s[4:7], s58 offen lds
	s_mov_b32 m0, s74
	s_nop 0
	buffer_load_dwordx4 v149, s[4:7], s58 offen lds
	s_waitcnt lgkmcnt(0)
	s_setprio 1
	s_barrier
	v_mfma_f32_16x16x32_bf16 v[138:141], v[54:57], v[232:235], v[138:141]
	v_mfma_f32_16x16x32_bf16 v[142:145], v[54:57], v[240:243], v[142:145]
	v_mfma_f32_16x16x32_bf16 v[134:137], v[174:177], v[232:235], v[134:137]
	v_mfma_f32_16x16x32_bf16 v[130:133], v[174:177], v[240:243], v[130:133]
	v_mfma_f32_16x16x32_bf16 v[126:129], v[182:185], v[232:235], v[126:129]
	v_mfma_f32_16x16x32_bf16 v[122:125], v[182:185], v[240:243], v[122:125]
	v_mfma_f32_16x16x32_bf16 v[118:121], v[190:193], v[232:235], v[118:121]
	v_mfma_f32_16x16x32_bf16 v[114:117], v[190:193], v[240:243], v[114:117]
	v_mfma_f32_16x16x32_bf16 v[138:141], v[170:173], v[236:239], v[138:141]
	v_mfma_f32_16x16x32_bf16 v[142:145], v[170:173], v[244:247], v[142:145]
	v_mfma_f32_16x16x32_bf16 v[134:137], v[178:181], v[236:239], v[134:137]
	v_mfma_f32_16x16x32_bf16 v[130:133], v[178:181], v[244:247], v[130:133]
	v_mfma_f32_16x16x32_bf16 v[126:129], v[186:189], v[236:239], v[126:129]
	v_mfma_f32_16x16x32_bf16 v[122:125], v[186:189], v[244:247], v[122:125]
	v_mfma_f32_16x16x32_bf16 v[118:121], v[194:197], v[236:239], v[118:121]
	v_mfma_f32_16x16x32_bf16 v[114:117], v[194:197], v[244:247], v[114:117]
	v_mfma_f32_16x16x32_bf16 v[110:113], v[54:57], v[204:207], v[110:113]
	v_mfma_f32_16x16x32_bf16 v[54:57], v[54:57], v[212:215], v[106:109]
	v_mfma_f32_16x16x32_bf16 v[106:109], v[170:173], v[216:219], v[54:57]
	v_mfma_f32_16x16x32_bf16 v[54:57], v[174:177], v[204:207], v[102:105]
	v_mfma_f32_16x16x32_bf16 v[102:105], v[178:181], v[208:211], v[54:57]
	v_mfma_f32_16x16x32_bf16 v[54:57], v[174:177], v[212:215], v[98:101]
	v_mfma_f32_16x16x32_bf16 v[98:101], v[178:181], v[216:219], v[54:57]
	v_mfma_f32_16x16x32_bf16 v[54:57], v[182:185], v[204:207], v[94:97]
	v_mfma_f32_16x16x32_bf16 v[94:97], v[186:189], v[208:211], v[54:57]
	v_mfma_f32_16x16x32_bf16 v[54:57], v[182:185], v[212:215], v[90:93]
	v_mfma_f32_16x16x32_bf16 v[90:93], v[186:189], v[216:219], v[54:57]
	v_mfma_f32_16x16x32_bf16 v[54:57], v[190:193], v[204:207], v[86:89]
	v_mfma_f32_16x16x32_bf16 v[86:89], v[194:197], v[208:211], v[54:57]
	v_mfma_f32_16x16x32_bf16 v[54:57], v[190:193], v[212:215], v[82:85]
	v_mfma_f32_16x16x32_bf16 v[110:113], v[170:173], v[208:211], v[110:113]
	v_mfma_f32_16x16x32_bf16 v[82:85], v[194:197], v[216:219], v[54:57]
	s_waitcnt vmcnt(8)
	s_barrier
	s_setprio 0
	s_addk_i32 s40, 0x180
	s_mov_b32 m0, s83
	ds_read_b128 v[170:173], v163 offset:49152
	ds_read_b128 v[174:177], v163 offset:50176
	ds_read_b128 v[178:181], v164 offset:49152
	ds_read_b128 v[182:185], v164 offset:50176
	ds_read_b128 v[186:189], v165 offset:49152
	ds_read_b128 v[190:193], v165 offset:50176
	ds_read_b128 v[194:197], v166 offset:49152
	ds_read_b128 v[220:223], v166 offset:50176
	buffer_load_dwordx4 v148, s[8:11], s40 offen lds
	s_mov_b32 m0, s82
	s_nop 0
	buffer_load_dwordx4 v149, s[8:11], s40 offen lds
	s_mov_b32 m0, s69
	s_addk_i32 s33, 0x180
	buffer_load_dwordx4 v148, s[4:7], s33 offen lds
	s_mov_b32 m0, s68
	s_nop 0
	buffer_load_dwordx4 v149, s[4:7], s33 offen lds
	ds_read_b128 v[2:5], v162
	ds_read_b128 v[6:9], v162 offset:1024
	ds_read_b128 v[10:13], v162 offset:2048
	ds_read_b128 v[14:17], v162 offset:3072
	s_addk_i32 s99, 0x100
	s_cmp_lt_i32 vcc_lo, s0
	s_waitcnt lgkmcnt(0)
	s_setprio 1
	s_barrier
	v_mfma_f32_16x16x32_bf16 v[54:57], v[170:173], v[232:235], v[78:81]
	v_mfma_f32_16x16x32_bf16 v[78:81], v[174:177], v[236:239], v[54:57]
	v_mfma_f32_16x16x32_bf16 v[54:57], v[170:173], v[240:243], v[74:77]
	v_mfma_f32_16x16x32_bf16 v[74:77], v[174:177], v[244:247], v[54:57]
	v_mfma_f32_16x16x32_bf16 v[54:57], v[178:181], v[232:235], v[70:73]
	v_mfma_f32_16x16x32_bf16 v[70:73], v[182:185], v[236:239], v[54:57]
	v_mfma_f32_16x16x32_bf16 v[54:57], v[178:181], v[240:243], v[66:69]
	v_mfma_f32_16x16x32_bf16 v[66:69], v[182:185], v[244:247], v[54:57]
	v_mfma_f32_16x16x32_bf16 v[54:57], v[186:189], v[232:235], v[62:65]
	v_mfma_f32_16x16x32_bf16 v[62:65], v[190:193], v[236:239], v[54:57]
	v_mfma_f32_16x16x32_bf16 v[54:57], v[186:189], v[240:243], v[58:61]
	v_mfma_f32_16x16x32_bf16 v[248:251], v[194:197], v[232:235], v[248:251]
	v_mfma_f32_16x16x32_bf16 v[58:61], v[190:193], v[244:247], v[54:57]
	v_mfma_f32_16x16x32_bf16 v[54:57], v[220:223], v[236:239], v[248:251]
	v_mfma_f32_16x16x32_bf16 v[248:251], v[194:197], v[240:243], v[252:255]
	v_mfma_f32_16x16x32_bf16 v[50:53], v[220:223], v[244:247], v[248:251]
	v_mfma_f32_16x16x32_bf16 v[46:49], v[170:173], v[204:207], v[46:49]
	v_mfma_f32_16x16x32_bf16 v[42:45], v[170:173], v[212:215], v[42:45]
	v_mfma_f32_16x16x32_bf16 v[38:41], v[178:181], v[204:207], v[38:41]
	v_mfma_f32_16x16x32_bf16 v[34:37], v[178:181], v[212:215], v[34:37]
	v_mfma_f32_16x16x32_bf16 v[30:33], v[186:189], v[204:207], v[30:33]
	v_mfma_f32_16x16x32_bf16 v[26:29], v[186:189], v[212:215], v[26:29]
	v_mfma_f32_16x16x32_bf16 v[22:25], v[194:197], v[204:207], v[22:25]
	v_mfma_f32_16x16x32_bf16 v[18:21], v[194:197], v[212:215], v[18:21]
	v_mfma_f32_16x16x32_bf16 v[46:49], v[174:177], v[208:211], v[46:49]
	v_mfma_f32_16x16x32_bf16 v[42:45], v[174:177], v[216:219], v[42:45]
	v_mfma_f32_16x16x32_bf16 v[38:41], v[182:185], v[208:211], v[38:41]
	v_mfma_f32_16x16x32_bf16 v[34:37], v[182:185], v[216:219], v[34:37]
	v_mfma_f32_16x16x32_bf16 v[30:33], v[190:193], v[208:211], v[30:33]
	v_mfma_f32_16x16x32_bf16 v[26:29], v[190:193], v[216:219], v[26:29]
	v_mfma_f32_16x16x32_bf16 v[22:25], v[220:223], v[208:211], v[22:25]
	v_mfma_f32_16x16x32_bf16 v[18:21], v[220:223], v[216:219], v[18:21]
	s_waitcnt vmcnt(8)
	s_barrier
	s_setprio 0
	s_cbranch_scc1 .LBB0_308
